# FF1 K-loop: LDS-DMA staging rebalanced from 2/6/2/6 to 4/4/4/4 loads per phase
# speedup vs baseline: 1.0001x; 1.0001x over previous
.LBB0_1679:
	s_lshl_b32 s13, s13, 5
	s_and_b32 s56, s13, 0x60
	s_add_i32 m0, s41, 0x18000
	v_lshl_add_u64 v[6:7], v[6:7], 0, s[26:27]
	s_lshl_b32 s55, s14, 6
	s_lshl_b32 s16, s14, 13
	s_lshl_b32 s13, s56, 7
	s_waitcnt vmcnt(2)
	s_barrier
	global_load_lds_dwordx4 v[6:7], off
	v_lshl_add_u64 v[4:5], v[4:5], 0, s[26:27]
	s_add_i32 m0, s41, 0x1a000
	s_add_i32 s57, s41, 0x8000
	s_add_i32 s58, s41, 0xa000
	global_load_lds_dwordx4 v[4:5], off
	v_lshl_add_u64 v[0:1], v[0:1], 0, s[26:27]
	s_mov_b32 m0, s57
	s_add_u32 s14, s36, 0x40080
	global_load_lds_dwordx4 v[0:1], off
	v_lshl_add_u64 v[0:1], v[2:3], 0, s[26:27]
	s_mov_b32 m0, s58
	s_addc_u32 s15, s37, 0
	global_load_lds_dwordx4 v[0:1], off
	s_movk_i32 s14, 0x3c0
	v_and_b32_e32 v0, 48, v8
	v_lshlrev_b32_e32 v1, 6, v8
	v_and_or_b32 v0, v1, s14, v0
	v_lshlrev_b32_e32 v1, 2, v8
	v_and_b32_e32 v1, 32, v1
	v_bitop3_b32 v2, v0, s16, v1 bitop3:0xde
	v_bitop3_b32 v142, s13, v0, v1 bitop3:0xf6
	v_lshlrev_b32_e32 v0, 14, v9
	v_and_b32_e32 v0, 0xffff8000, v0
	v_lshl_add_u32 v0, v10, 11, v0
	v_and_b32_e32 v1, 1, v9
	v_lshl_or_b32 v0, v1, 6, v0
	v_lshl_add_u32 v136, v11, 1, v0
	v_lshlrev_b32_e32 v0, 14, v13
	v_and_b32_e32 v0, 0xffff8000, v0
	s_waitcnt vmcnt(4)
	v_lshl_add_u32 v0, v12, 11, v0
	v_and_b32_e32 v1, 1, v13
	s_cmpk_lt_u32 s12, 0x100
	v_lshl_or_b32 v0, v1, 6, v0
	s_cselect_b64 s[12:13], -1, 0
	v_mov_b32_e32 v137, v113
	v_lshl_add_u32 v138, v14, 1, v0
	v_mov_b32_e32 v139, v113
	s_mov_b32 s59, 0
	v_add_u32_e32 v143, 0, v2
	s_barrier
	s_branch .LBB0_1682

.LBB0_1685:
	s_add_u32 s46, s36, 0xfffc0080
	s_addc_u32 s47, s37, -1
	s_add_i32 s65, 0, 0x10000
	s_cmp_eq_u32 s64, 12
	s_cselect_b32 s49, s17, s47
	s_cselect_b32 s48, s60, s46
	v_add_u32_e32 v140, s65, v142
	s_cselect_b32 s47, s15, s63
	s_cselect_b32 s46, s61, s62
	s_add_i32 s68, 0, 0x14000
	ds_read_b128 v[162:165], v140
	ds_read_b128 v[166:169], v140 offset:1024
	ds_read_b128 v[170:173], v140 offset:2048
	ds_read_b128 v[174:177], v140 offset:3072
	v_add_u32_e32 v140, s68, v142
	ds_read_b128 v[178:181], v140
	ds_read_b128 v[202:205], v140 offset:1024
	ds_read_b128 v[206:209], v140 offset:2048
	ds_read_b128 v[210:213], v140 offset:3072
	s_add_u32 s98, s62, 0x3ff80
	s_addc_u32 s99, s63, 0
	v_lshl_add_u64 v[140:141], s[98:99], 0, v[112:113]
	s_add_i32 m0, s51, 0x1c000
	s_nop 0
	global_load_lds_dwordx4 v[140:141], off
	v_lshl_add_u64 v[140:141], s[98:99], 0, v[130:131]
	s_add_i32 m0, m0, 0x2000
	s_nop 0
	global_load_lds_dwordx4 v[140:141], off
	v_lshl_add_u64 v[140:141], s[36:37], 0, v[138:139]
	s_add_i32 m0, s41, 0xc000
	ds_read_b128 v[214:217], v143
	ds_read_b128 v[218:221], v143 offset:1024
	ds_read_b128 v[222:225], v143 offset:2048
	ds_read_b128 v[226:229], v143 offset:3072
	ds_read_b128 v[230:233], v143 offset:4096
	ds_read_b128 v[234:237], v143 offset:5120
	ds_read_b128 v[238:241], v143 offset:6144
	ds_read_b128 v[242:245], v143 offset:7168
	global_load_lds_dwordx4 v[140:141], off
	v_lshl_add_u64 v[140:141], s[36:37], 0, v[136:137]
	s_add_i32 m0, s41, 0xe000
	s_nop 0
	global_load_lds_dwordx4 v[140:141], off
	s_waitcnt vmcnt(8)
	s_waitcnt lgkmcnt(0)
	s_barrier
	s_setprio 1
	s_waitcnt lgkmcnt(0)
	v_mfma_f32_16x16x32_bf16 v[126:129], v[162:165], v[214:217], v[126:129]
	v_mfma_f32_16x16x32_bf16 v[122:125], v[170:173], v[214:217], v[122:125]
	v_mfma_f32_16x16x32_bf16 v[108:111], v[162:165], v[222:225], v[108:111]
	v_mfma_f32_16x16x32_bf16 v[104:107], v[170:173], v[222:225], v[104:107]
	v_mfma_f32_16x16x32_bf16 v[92:95], v[162:165], v[230:233], v[92:95]
	v_mfma_f32_16x16x32_bf16 v[88:91], v[170:173], v[230:233], v[88:91]
	v_mfma_f32_16x16x32_bf16 v[76:79], v[162:165], v[238:241], v[76:79]
	v_mfma_f32_16x16x32_bf16 v[72:75], v[170:173], v[238:241], v[72:75]
	v_mfma_f32_16x16x32_bf16 v[126:129], v[166:169], v[218:221], v[126:129]
	v_mfma_f32_16x16x32_bf16 v[122:125], v[174:177], v[218:221], v[122:125]
	v_mfma_f32_16x16x32_bf16 v[108:111], v[166:169], v[226:229], v[108:111]
	v_mfma_f32_16x16x32_bf16 v[104:107], v[174:177], v[226:229], v[104:107]
	v_mfma_f32_16x16x32_bf16 v[92:95], v[166:169], v[234:237], v[92:95]
	v_mfma_f32_16x16x32_bf16 v[88:91], v[174:177], v[234:237], v[88:91]
	v_mfma_f32_16x16x32_bf16 v[76:79], v[166:169], v[242:245], v[76:79]
	v_mfma_f32_16x16x32_bf16 v[72:75], v[174:177], v[242:245], v[72:75]
	s_setprio 0
	s_setprio 1
	v_mfma_f32_16x16x32_bf16 v[118:121], v[178:181], v[214:217], v[118:121]
	v_mfma_f32_16x16x32_bf16 v[114:117], v[206:209], v[214:217], v[114:117]
	v_mfma_f32_16x16x32_bf16 v[100:103], v[178:181], v[222:225], v[100:103]
	v_mfma_f32_16x16x32_bf16 v[96:99], v[206:209], v[222:225], v[96:99]
	v_mfma_f32_16x16x32_bf16 v[84:87], v[178:181], v[230:233], v[84:87]
	v_mfma_f32_16x16x32_bf16 v[80:83], v[206:209], v[230:233], v[80:83]
	v_mfma_f32_16x16x32_bf16 v[68:71], v[178:181], v[238:241], v[68:71]
	v_mfma_f32_16x16x32_bf16 v[64:67], v[206:209], v[238:241], v[64:67]
	v_mfma_f32_16x16x32_bf16 v[118:121], v[202:205], v[218:221], v[118:121]
	v_mfma_f32_16x16x32_bf16 v[114:117], v[210:213], v[218:221], v[114:117]
	v_mfma_f32_16x16x32_bf16 v[100:103], v[202:205], v[226:229], v[100:103]
	v_mfma_f32_16x16x32_bf16 v[96:99], v[210:213], v[226:229], v[96:99]
	v_mfma_f32_16x16x32_bf16 v[84:87], v[202:205], v[234:237], v[84:87]
	v_mfma_f32_16x16x32_bf16 v[80:83], v[210:213], v[234:237], v[80:83]
	v_mfma_f32_16x16x32_bf16 v[68:71], v[202:205], v[242:245], v[68:71]
	v_mfma_f32_16x16x32_bf16 v[64:67], v[210:213], v[242:245], v[64:67]
	s_setprio 0
	s_barrier
	s_add_i32 s65, s65, s51
	v_lshl_add_u64 v[140:141], s[46:47], 0, v[112:113]
	s_mov_b32 m0, s65
	ds_read_b128 v[214:217], v143 offset:16384
	ds_read_b128 v[218:221], v143 offset:17408
	ds_read_b128 v[222:225], v143 offset:18432
	ds_read_b128 v[226:229], v143 offset:19456
	ds_read_b128 v[230:233], v143 offset:20480
	ds_read_b128 v[234:237], v143 offset:21504
	ds_read_b128 v[238:241], v143 offset:22528
	ds_read_b128 v[242:245], v143 offset:23552
	global_load_lds_dwordx4 v[140:141], off
	s_add_i32 m0, s65, 0x2000
	s_add_u32 s66, s46, 0x40000
	v_lshl_add_u64 v[144:145], s[46:47], 0, v[130:131]
	s_addc_u32 s67, s47, 0
	s_add_i32 s65, s68, s51
	global_load_lds_dwordx4 v[144:145], off
	v_lshl_add_u64 v[148:149], s[48:49], 0, v[132:133]
	v_lshl_add_u64 v[146:147], s[48:49], 0, v[134:135]
	s_mov_b32 m0, s41
	s_nop 0
	global_load_lds_dwordx4 v[146:147], off
	s_mov_b32 m0, s45
	s_nop 0
	global_load_lds_dwordx4 v[148:149], off
	s_waitcnt vmcnt(6)
	s_waitcnt lgkmcnt(0)
	s_barrier
	s_setprio 1
	s_waitcnt lgkmcnt(0)
	v_mfma_f32_16x16x32_bf16 v[60:63], v[162:165], v[214:217], v[60:63]
	v_mfma_f32_16x16x32_bf16 v[56:59], v[170:173], v[214:217], v[56:59]
	v_mfma_f32_16x16x32_bf16 v[44:47], v[162:165], v[222:225], v[44:47]
	v_mfma_f32_16x16x32_bf16 v[40:43], v[170:173], v[222:225], v[40:43]
	v_mfma_f32_16x16x32_bf16 v[28:31], v[162:165], v[230:233], v[28:31]
	v_mfma_f32_16x16x32_bf16 v[24:27], v[170:173], v[230:233], v[24:27]
	v_mfma_f32_16x16x32_bf16 v[12:15], v[162:165], v[238:241], v[12:15]
	v_mfma_f32_16x16x32_bf16 v[8:11], v[170:173], v[238:241], v[8:11]
	v_mfma_f32_16x16x32_bf16 v[60:63], v[166:169], v[218:221], v[60:63]
	v_mfma_f32_16x16x32_bf16 v[56:59], v[174:177], v[218:221], v[56:59]
	v_mfma_f32_16x16x32_bf16 v[44:47], v[166:169], v[226:229], v[44:47]
	v_mfma_f32_16x16x32_bf16 v[40:43], v[174:177], v[226:229], v[40:43]
	v_mfma_f32_16x16x32_bf16 v[28:31], v[166:169], v[234:237], v[28:31]
	v_mfma_f32_16x16x32_bf16 v[24:27], v[174:177], v[234:237], v[24:27]
	v_mfma_f32_16x16x32_bf16 v[12:15], v[166:169], v[242:245], v[12:15]
	v_mfma_f32_16x16x32_bf16 v[8:11], v[174:177], v[242:245], v[8:11]
	s_setprio 0
	s_setprio 1
	v_mfma_f32_16x16x32_bf16 v[52:55], v[178:181], v[214:217], v[52:55]
	v_mfma_f32_16x16x32_bf16 v[48:51], v[206:209], v[214:217], v[48:51]
	v_mfma_f32_16x16x32_bf16 v[36:39], v[178:181], v[222:225], v[36:39]
	v_mfma_f32_16x16x32_bf16 v[32:35], v[206:209], v[222:225], v[32:35]
	v_mfma_f32_16x16x32_bf16 v[20:23], v[178:181], v[230:233], v[20:23]
	v_mfma_f32_16x16x32_bf16 v[16:19], v[206:209], v[230:233], v[16:19]
	v_mfma_f32_16x16x32_bf16 v[4:7], v[178:181], v[238:241], v[4:7]
	v_mfma_f32_16x16x32_bf16 v[0:3], v[206:209], v[238:241], v[0:3]
	v_mfma_f32_16x16x32_bf16 v[52:55], v[202:205], v[218:221], v[52:55]
	v_mfma_f32_16x16x32_bf16 v[48:51], v[210:213], v[218:221], v[48:51]
	v_mfma_f32_16x16x32_bf16 v[36:39], v[202:205], v[226:229], v[36:39]
	v_mfma_f32_16x16x32_bf16 v[32:35], v[210:213], v[226:229], v[32:35]
	v_mfma_f32_16x16x32_bf16 v[20:23], v[202:205], v[234:237], v[20:23]
	v_mfma_f32_16x16x32_bf16 v[16:19], v[210:213], v[234:237], v[16:19]
	v_mfma_f32_16x16x32_bf16 v[4:7], v[202:205], v[242:245], v[4:7]
	v_mfma_f32_16x16x32_bf16 v[0:3], v[210:213], v[242:245], v[0:3]
	s_setprio 0
	s_barrier
	s_add_i32 s65, 0, 0x18000
	v_add_u32_e32 v150, s65, v142
	s_add_i32 s66, 0, 0x1c000
	ds_read_b128 v[162:165], v150
	ds_read_b128 v[166:169], v150 offset:1024
	ds_read_b128 v[170:173], v150 offset:2048
	ds_read_b128 v[174:177], v150 offset:3072
	v_add_u32_e32 v150, s66, v142
	ds_read_b128 v[178:181], v150
	ds_read_b128 v[202:205], v150 offset:1024
	ds_read_b128 v[206:209], v150 offset:2048
	ds_read_b128 v[210:213], v150 offset:3072
	s_add_u32 s98, s46, 0x40000
	s_addc_u32 s99, s47, 0
	v_lshl_add_u64 v[150:151], s[98:99], 0, v[112:113]
	s_add_i32 m0, s68, s51
	s_nop 0
	global_load_lds_dwordx4 v[150:151], off
	v_lshl_add_u64 v[150:151], s[98:99], 0, v[130:131]
	s_add_i32 m0, m0, 0x2000
	s_nop 0
	global_load_lds_dwordx4 v[150:151], off
	s_add_u32 s48, s48, 0x40000
	s_addc_u32 s49, s49, 0
	s_mov_b32 m0, s53
	v_lshl_add_u64 v[150:151], s[48:49], 0, v[134:135]
	ds_read_b128 v[214:217], v143 offset:32768
	ds_read_b128 v[218:221], v143 offset:33792
	ds_read_b128 v[222:225], v143 offset:34816
	ds_read_b128 v[226:229], v143 offset:35840
	ds_read_b128 v[230:233], v143 offset:36864
	ds_read_b128 v[234:237], v143 offset:37888
	ds_read_b128 v[238:241], v143 offset:38912
	ds_read_b128 v[242:245], v143 offset:39936
	global_load_lds_dwordx4 v[150:151], off
	v_lshl_add_u64 v[150:151], s[48:49], 0, v[132:133]
	s_mov_b32 m0, s54
	s_nop 0
	global_load_lds_dwordx4 v[150:151], off
	s_waitcnt vmcnt(8)
	s_waitcnt lgkmcnt(0)
	s_barrier
	s_setprio 1
	s_waitcnt lgkmcnt(0)
	v_mfma_f32_16x16x32_bf16 v[126:129], v[162:165], v[214:217], v[126:129]
	v_mfma_f32_16x16x32_bf16 v[122:125], v[170:173], v[214:217], v[122:125]
	v_mfma_f32_16x16x32_bf16 v[108:111], v[162:165], v[222:225], v[108:111]
	v_mfma_f32_16x16x32_bf16 v[104:107], v[170:173], v[222:225], v[104:107]
	v_mfma_f32_16x16x32_bf16 v[92:95], v[162:165], v[230:233], v[92:95]
	v_mfma_f32_16x16x32_bf16 v[88:91], v[170:173], v[230:233], v[88:91]
	v_mfma_f32_16x16x32_bf16 v[76:79], v[162:165], v[238:241], v[76:79]
	v_mfma_f32_16x16x32_bf16 v[72:75], v[170:173], v[238:241], v[72:75]
	v_mfma_f32_16x16x32_bf16 v[126:129], v[166:169], v[218:221], v[126:129]
	v_mfma_f32_16x16x32_bf16 v[122:125], v[174:177], v[218:221], v[122:125]
	v_mfma_f32_16x16x32_bf16 v[108:111], v[166:169], v[226:229], v[108:111]
	v_mfma_f32_16x16x32_bf16 v[104:107], v[174:177], v[226:229], v[104:107]
	v_mfma_f32_16x16x32_bf16 v[92:95], v[166:169], v[234:237], v[92:95]
	v_mfma_f32_16x16x32_bf16 v[88:91], v[174:177], v[234:237], v[88:91]
	v_mfma_f32_16x16x32_bf16 v[76:79], v[166:169], v[242:245], v[76:79]
	v_mfma_f32_16x16x32_bf16 v[72:75], v[174:177], v[242:245], v[72:75]
	s_setprio 0
	s_setprio 1
	v_mfma_f32_16x16x32_bf16 v[118:121], v[178:181], v[214:217], v[118:121]
	v_mfma_f32_16x16x32_bf16 v[114:117], v[206:209], v[214:217], v[114:117]
	v_mfma_f32_16x16x32_bf16 v[100:103], v[178:181], v[222:225], v[100:103]
	v_mfma_f32_16x16x32_bf16 v[96:99], v[206:209], v[222:225], v[96:99]
	v_mfma_f32_16x16x32_bf16 v[84:87], v[178:181], v[230:233], v[84:87]
	v_mfma_f32_16x16x32_bf16 v[80:83], v[206:209], v[230:233], v[80:83]
	v_mfma_f32_16x16x32_bf16 v[68:71], v[178:181], v[238:241], v[68:71]
	v_mfma_f32_16x16x32_bf16 v[64:67], v[206:209], v[238:241], v[64:67]
	v_mfma_f32_16x16x32_bf16 v[118:121], v[202:205], v[218:221], v[118:121]
	v_mfma_f32_16x16x32_bf16 v[114:117], v[210:213], v[218:221], v[114:117]
	v_mfma_f32_16x16x32_bf16 v[100:103], v[202:205], v[226:229], v[100:103]
	v_mfma_f32_16x16x32_bf16 v[96:99], v[210:213], v[226:229], v[96:99]
	v_mfma_f32_16x16x32_bf16 v[84:87], v[202:205], v[234:237], v[84:87]
	v_mfma_f32_16x16x32_bf16 v[80:83], v[210:213], v[234:237], v[80:83]
	v_mfma_f32_16x16x32_bf16 v[68:71], v[202:205], v[242:245], v[68:71]
	v_mfma_f32_16x16x32_bf16 v[64:67], v[210:213], v[242:245], v[64:67]
	s_setprio 0
	s_barrier
	s_add_i32 s48, s65, s51
	v_lshl_add_u64 v[140:141], v[140:141], 0, s[26:27]
	s_mov_b32 m0, s48
	ds_read_b128 v[214:217], v143 offset:49152
	ds_read_b128 v[218:221], v143 offset:50176
	ds_read_b128 v[222:225], v143 offset:51200
	ds_read_b128 v[226:229], v143 offset:52224
	ds_read_b128 v[230:233], v143 offset:53248
	ds_read_b128 v[234:237], v143 offset:54272
	ds_read_b128 v[238:241], v143 offset:55296
	ds_read_b128 v[242:245], v143 offset:56320
	global_load_lds_dwordx4 v[140:141], off
	s_add_i32 m0, s48, 0x2000
	s_add_u32 s46, s46, 0x40080
	v_lshl_add_u64 v[140:141], v[144:145], 0, s[26:27]
	s_addc_u32 s47, s47, 0
	s_add_i32 s48, s66, s51
	global_load_lds_dwordx4 v[140:141], off
	v_lshl_add_u64 v[140:141], v[146:147], 0, s[26:27]
	s_mov_b32 m0, s57
	s_nop 0
	global_load_lds_dwordx4 v[140:141], off
	v_lshl_add_u64 v[140:141], v[148:149], 0, s[26:27]
	s_mov_b32 m0, s58
	s_nop 0
	global_load_lds_dwordx4 v[140:141], off
	s_waitcnt vmcnt(6)
	s_waitcnt lgkmcnt(0)
	s_barrier
	s_setprio 1
	s_waitcnt lgkmcnt(0)
	v_mfma_f32_16x16x32_bf16 v[60:63], v[162:165], v[214:217], v[60:63]
	v_mfma_f32_16x16x32_bf16 v[56:59], v[170:173], v[214:217], v[56:59]
	v_mfma_f32_16x16x32_bf16 v[44:47], v[162:165], v[222:225], v[44:47]
	v_mfma_f32_16x16x32_bf16 v[40:43], v[170:173], v[222:225], v[40:43]
	v_mfma_f32_16x16x32_bf16 v[28:31], v[162:165], v[230:233], v[28:31]
	v_mfma_f32_16x16x32_bf16 v[24:27], v[170:173], v[230:233], v[24:27]
	v_mfma_f32_16x16x32_bf16 v[12:15], v[162:165], v[238:241], v[12:15]
	v_mfma_f32_16x16x32_bf16 v[8:11], v[170:173], v[238:241], v[8:11]
	v_mfma_f32_16x16x32_bf16 v[60:63], v[166:169], v[218:221], v[60:63]
	v_mfma_f32_16x16x32_bf16 v[56:59], v[174:177], v[218:221], v[56:59]
	v_mfma_f32_16x16x32_bf16 v[44:47], v[166:169], v[226:229], v[44:47]
	v_mfma_f32_16x16x32_bf16 v[40:43], v[174:177], v[226:229], v[40:43]
	v_mfma_f32_16x16x32_bf16 v[28:31], v[166:169], v[234:237], v[28:31]
	v_mfma_f32_16x16x32_bf16 v[24:27], v[174:177], v[234:237], v[24:27]
	v_mfma_f32_16x16x32_bf16 v[12:15], v[166:169], v[242:245], v[12:15]
	v_mfma_f32_16x16x32_bf16 v[8:11], v[174:177], v[242:245], v[8:11]
	s_setprio 0
	s_setprio 1
	v_mfma_f32_16x16x32_bf16 v[52:55], v[178:181], v[214:217], v[52:55]
	v_mfma_f32_16x16x32_bf16 v[48:51], v[206:209], v[214:217], v[48:51]
	v_mfma_f32_16x16x32_bf16 v[36:39], v[178:181], v[222:225], v[36:39]
	v_mfma_f32_16x16x32_bf16 v[32:35], v[206:209], v[222:225], v[32:35]
	v_mfma_f32_16x16x32_bf16 v[20:23], v[178:181], v[230:233], v[20:23]
	v_mfma_f32_16x16x32_bf16 v[16:19], v[206:209], v[230:233], v[16:19]
	v_mfma_f32_16x16x32_bf16 v[4:7], v[178:181], v[238:241], v[4:7]
	v_mfma_f32_16x16x32_bf16 v[0:3], v[206:209], v[238:241], v[0:3]
	v_mfma_f32_16x16x32_bf16 v[52:55], v[202:205], v[218:221], v[52:55]
	v_mfma_f32_16x16x32_bf16 v[48:51], v[210:213], v[218:221], v[48:51]
	v_mfma_f32_16x16x32_bf16 v[36:39], v[202:205], v[226:229], v[36:39]
	v_mfma_f32_16x16x32_bf16 v[32:35], v[210:213], v[226:229], v[32:35]
	v_mfma_f32_16x16x32_bf16 v[20:23], v[202:205], v[234:237], v[20:23]
	v_mfma_f32_16x16x32_bf16 v[16:19], v[210:213], v[234:237], v[16:19]
	v_mfma_f32_16x16x32_bf16 v[4:7], v[202:205], v[242:245], v[4:7]
	v_mfma_f32_16x16x32_bf16 v[0:3], v[210:213], v[242:245], v[0:3]
	s_setprio 0
	s_barrier
	s_add_i32 s64, s64, 2
	s_add_u32 s62, s62, 0x100
	s_addc_u32 s63, s63, 0
	s_add_u32 s36, s36, 0x100
	s_addc_u32 s37, s37, 0
	s_cmp_gt_u32 s64, 13
	s_cbranch_scc0 .LBB0_1685
	s_and_b64 vcc, exec, s[12:13]
	s_cbranch_vccz .LBB0_1688
	s_barrier
